# stack25: stack23 + cmp gate element requested at unit start + cmp importance LDS reads issued together before the masked selection blocks
# speedup vs baseline: 1.0129x; 1.0129x over previous
.LBB0_1301:
	s_ashr_i32 s0, s24, 2
	s_lshl_b32 s30, s33, 6
	s_lshl_b32 s1, s24, 2
	v_add_u32_e32 v18, s30, v177
	v_and_or_b32 v232, s1, 12, v178
	s_ashr_i32 s1, s0, 31
	s_lshl_b64 s[0:1], s[0:1], 13
	v_ashrrev_i32_e32 v19, 31, v18
	v_lshl_add_u64 v[154:155], s[0:1], 0, v[18:19]
	v_mov_b64_e32 v[2:3], s[82:83]
	v_mad_u64_u32 v[158:159], s[0:1], v154, s21, v[2:3]
	v_mad_i32_i24 v159, v155, s21, v159
	v_lshlrev_b32_e32 v146, 7, v232
	v_lshl_add_u64 v[2:3], v[158:159], 0, v[146:147]
	v_lshl_add_u64 v[2:3], v[138:139], 1, v[2:3]
	s_mov_b64 s[0:1], 0x1800
	v_lshl_add_u64 v[4:5], v[2:3], 0, s[0:1]
	v_add_co_u32_e32 v2, vcc, 0x1000, v2
	v_lshlrev_b32_e32 v156, 6, v232
	s_nop 0
	v_addc_co_u32_e32 v3, vcc, 0, v3, vcc
	global_load_dwordx4 v[86:89], v[4:5], off offset:32
	global_load_dwordx4 v[90:93], v[4:5], off offset:64
	global_load_dwordx4 v[94:97], v[2:3], off offset:2048
	global_load_dwordx4 v[98:101], v[4:5], off offset:96
	v_mul_u32_u24_e32 v241, 3, v232
	v_lshlrev_b32_e32 v242, 1, v241
	v_mov_b32_e32 v243, 0
	v_lshl_add_u64 v[242:243], v[158:159], 0, v[242:243]
	v_add_co_u32_e32 v242, vcc, 0x3000, v242
	s_nop 1
	v_addc_co_u32_e32 v243, vcc, 0, v243, vcc
	global_load_ushort v241, v[242:243], off offset:3104
	s_mov_b64 s[0:1], 0
	v_mov_b32_e32 v2, v172
	v_mov_b32_e32 v3, v202

.LBB0_1364:
	ds_read_b32 v106, v182 offset:39008
	ds_read_b32 v107, v182 offset:39012
	ds_read_b32 v108, v182 offset:39016
	ds_read_b32 v109, v182 offset:39020
	ds_read_b32 v110, v182 offset:39024
	ds_read_b32 v111, v182 offset:39028
	ds_read_b32 v112, v182 offset:39032
	ds_read_b32 v113, v182 offset:39036
	ds_read_b32 v114, v182 offset:39040
	ds_read_b32 v115, v182 offset:39044
	ds_read_b32 v116, v182 offset:39048
	ds_read_b32 v117, v182 offset:39052
	ds_read_b32 v118, v182 offset:39056
	ds_read_b32 v119, v182 offset:39060
	ds_read_b32 v120, v182 offset:39064
	ds_read_b32 v121, v182 offset:39068
	v_lshlrev_b64 v[4:5], 11, v[154:155]
	v_lshl_add_u64 v[4:5], s[16:17], 0, v[4:5]
	v_lshlrev_b32_e32 v146, 1, v156
	v_lshl_add_u64 v[4:5], v[4:5], 0, v[146:147]
	v_lshl_add_u64 v[4:5], v[140:141], 1, v[4:5]
	v_readlane_b32 s0, v247, 20
	s_add_i32 s4, s33, -1
	v_cmp_eq_u32_e32 vcc, s33, v181
	v_readlane_b32 s1, v247, 21
	s_or_b64 s[0:1], s[0:1], vcc
	v_cmp_eq_u32_e32 vcc, s4, v181
	s_or_b64 s[6:7], s[0:1], vcc
	v_cmp_lt_i32_e64 s[8:9], s33, v181
	s_nor_b64 s[0:1], s[8:9], s[6:7]
	s_waitcnt vmcnt(0)
	v_lshlrev_b32_e32 v2, 16, v241
	v_mul_f32_e32 v2, 0xbfb8aa3b, v2
	v_exp_f32_e32 v2, v2
	s_nop 0
	v_add_f32_e32 v2, 1.0, v2
	v_rcp_f32_e32 v2, v2
	s_nop 0
	v_pk_mul_f32 v[6:7], v[34:35], v[2:3] op_sel_hi:[1,0]
	v_pk_mul_f32 v[8:9], v[36:37], v[2:3] op_sel_hi:[1,0]
	v_cvt_pk_bf16_f32 v6, v6, v7
	v_cvt_pk_bf16_f32 v7, v8, v9
	global_store_dwordx2 v[4:5], v[6:7], off
	v_pk_mul_f32 v[6:7], v[38:39], v[2:3] op_sel_hi:[1,0]
	v_pk_mul_f32 v[8:9], v[40:41], v[2:3] op_sel_hi:[1,0]
	v_cvt_pk_bf16_f32 v6, v6, v7
	v_cvt_pk_bf16_f32 v7, v8, v9
	global_store_dwordx2 v[4:5], v[6:7], off offset:16
	v_pk_mul_f32 v[6:7], v[42:43], v[2:3] op_sel_hi:[1,0]
	v_pk_mul_f32 v[8:9], v[44:45], v[2:3] op_sel_hi:[1,0]
	v_cvt_pk_bf16_f32 v6, v6, v7
	v_cvt_pk_bf16_f32 v7, v8, v9
	global_store_dwordx2 v[4:5], v[6:7], off offset:32
	v_pk_mul_f32 v[6:7], v[46:47], v[2:3] op_sel_hi:[1,0]
	v_pk_mul_f32 v[8:9], v[48:49], v[2:3] op_sel_hi:[1,0]
	v_cvt_pk_bf16_f32 v6, v6, v7
	v_cvt_pk_bf16_f32 v7, v8, v9
	global_store_dwordx2 v[4:5], v[6:7], off offset:48
	v_pk_mul_f32 v[6:7], v[18:19], v[2:3] op_sel_hi:[1,0]
	v_pk_mul_f32 v[8:9], v[20:21], v[2:3] op_sel_hi:[1,0]
	v_cvt_pk_bf16_f32 v6, v6, v7
	v_cvt_pk_bf16_f32 v7, v8, v9
	global_store_dwordx2 v[4:5], v[6:7], off offset:64
	v_pk_mul_f32 v[6:7], v[22:23], v[2:3] op_sel_hi:[1,0]
	v_pk_mul_f32 v[8:9], v[24:25], v[2:3] op_sel_hi:[1,0]
	v_cvt_pk_bf16_f32 v6, v6, v7
	v_cvt_pk_bf16_f32 v7, v8, v9
	global_store_dwordx2 v[4:5], v[6:7], off offset:80
	v_pk_mul_f32 v[6:7], v[26:27], v[2:3] op_sel_hi:[1,0]
	v_pk_mul_f32 v[8:9], v[28:29], v[2:3] op_sel_hi:[1,0]
	v_cvt_pk_bf16_f32 v6, v6, v7
	v_cvt_pk_bf16_f32 v7, v8, v9
	global_store_dwordx2 v[4:5], v[6:7], off offset:96
	v_pk_mul_f32 v[6:7], v[30:31], v[2:3] op_sel_hi:[1,0]
	v_pk_mul_f32 v[2:3], v[32:33], v[2:3] op_sel_hi:[1,0]
	v_cvt_pk_bf16_f32 v6, v6, v7
	v_cvt_pk_bf16_f32 v7, v2, v3
	v_mov_b32_e32 v2, 0
	v_mov_b32_e32 v3, 0
	global_store_dwordx2 v[4:5], v[6:7], off offset:112
	s_waitcnt lgkmcnt(0)
	s_and_saveexec_b64 s[2:3], s[0:1]
	s_cbranch_execz .LBB0_1366
	v_mov_b32_e32 v3, v106
	s_nop 0
	v_max_f32_e32 v3, v3, v3
	v_max_f32_e32 v3, 0, v3
	v_add_u32_e32 v3, 1, v3
.LBB0_1366:
	s_or_b64 exec, exec, s[2:3]
	v_cmp_eq_u32_e32 vcc, s33, v183
	v_cmp_eq_u32_e64 s[0:1], s4, v183
	s_or_b64 s[10:11], vcc, s[0:1]
	v_cmp_le_i32_e64 s[12:13], s33, v181
	s_nor_b64 s[2:3], s[12:13], s[10:11]
	s_and_saveexec_b64 s[0:1], s[2:3]
	s_cbranch_execz .LBB0_1368
	v_mov_b32_e32 v2, v107
	s_nop 0
	v_max_f32_e32 v2, v2, v2
	v_max_f32_e32 v2, 0, v2
	v_add_u32_e32 v2, 1, v2
.LBB0_1368:
	s_or_b64 exec, exec, s[0:1]
	v_cmp_eq_u32_e32 vcc, s33, v184
	v_cmp_eq_u32_e64 s[0:1], s4, v184
	s_or_b64 s[28:29], vcc, s[0:1]
	v_cmp_lt_i32_e64 s[34:35], s33, v184
	s_nor_b64 s[2:3], s[34:35], s[28:29]
	v_mov_b32_e32 v4, 0
	v_mov_b32_e32 v5, 0
	s_and_saveexec_b64 s[0:1], s[2:3]
	s_cbranch_execz .LBB0_1370
	v_mov_b32_e32 v5, v108
	s_nop 0
	v_max_f32_e32 v5, v5, v5
	v_max_f32_e32 v5, 0, v5
	v_add_u32_e32 v5, 1, v5
.LBB0_1370:
	s_or_b64 exec, exec, s[0:1]
	v_cmp_eq_u32_e32 vcc, s33, v185
	v_cmp_eq_u32_e64 s[0:1], s4, v185
	s_or_b64 s[36:37], vcc, s[0:1]
	v_cmp_lt_i32_e64 s[38:39], s33, v185
	s_nor_b64 s[2:3], s[38:39], s[36:37]
	s_and_saveexec_b64 s[0:1], s[2:3]
	s_cbranch_execz .LBB0_1372
	v_mov_b32_e32 v4, v109
	s_nop 0
	v_max_f32_e32 v4, v4, v4
	v_max_f32_e32 v4, 0, v4
	v_add_u32_e32 v4, 1, v4
.LBB0_1372:
	s_or_b64 exec, exec, s[0:1]
	v_cmp_eq_u32_e32 vcc, s33, v186
	v_cmp_eq_u32_e64 s[0:1], s4, v186
	s_or_b64 s[44:45], vcc, s[0:1]
	v_cmp_lt_i32_e64 s[46:47], s33, v186
	s_nor_b64 s[2:3], s[46:47], s[44:45]
	v_mov_b32_e32 v6, 0
	v_mov_b32_e32 v7, 0
	s_and_saveexec_b64 s[0:1], s[2:3]
	s_cbranch_execz .LBB0_1374
	v_mov_b32_e32 v7, v110
	s_nop 0
	v_max_f32_e32 v7, v7, v7
	v_max_f32_e32 v7, 0, v7
	v_add_u32_e32 v7, 1, v7
.LBB0_1374:
	s_or_b64 exec, exec, s[0:1]
	v_cmp_eq_u32_e32 vcc, s33, v187
	v_cmp_eq_u32_e64 s[0:1], s4, v187
	s_or_b64 s[52:53], vcc, s[0:1]
	v_cmp_lt_i32_e64 s[58:59], s33, v187
	s_nor_b64 s[2:3], s[58:59], s[52:53]
	s_and_saveexec_b64 s[0:1], s[2:3]
	s_cbranch_execz .LBB0_1376
	v_mov_b32_e32 v6, v111
	s_nop 0
	v_max_f32_e32 v6, v6, v6
	v_max_f32_e32 v6, 0, v6
	v_add_u32_e32 v6, 1, v6
.LBB0_1376:
	s_or_b64 exec, exec, s[0:1]
	v_cmp_eq_u32_e32 vcc, s33, v188
	v_cmp_eq_u32_e64 s[0:1], s4, v188
	s_or_b64 s[64:65], vcc, s[0:1]
	v_cmp_lt_i32_e64 s[66:67], s33, v188
	s_nor_b64 s[2:3], s[66:67], s[64:65]
	v_mov_b32_e32 v8, 0
	v_mov_b32_e32 v9, 0
	s_and_saveexec_b64 s[0:1], s[2:3]
	s_cbranch_execz .LBB0_1378
	v_mov_b32_e32 v9, v112
	s_nop 0
	v_max_f32_e32 v9, v9, v9
	v_max_f32_e32 v9, 0, v9
	v_add_u32_e32 v9, 1, v9
.LBB0_1378:
	s_or_b64 exec, exec, s[0:1]
	v_cmp_eq_u32_e32 vcc, s33, v190
	v_cmp_eq_u32_e64 s[0:1], s4, v190
	s_or_b64 s[68:69], vcc, s[0:1]
	v_cmp_lt_i32_e64 s[70:71], s33, v190
	s_nor_b64 s[2:3], s[70:71], s[68:69]
	s_and_saveexec_b64 s[0:1], s[2:3]
	s_cbranch_execz .LBB0_1380
	v_mov_b32_e32 v8, v113
	s_nop 0
	v_max_f32_e32 v8, v8, v8
	v_max_f32_e32 v8, 0, v8
	v_add_u32_e32 v8, 1, v8
.LBB0_1380:
	s_or_b64 exec, exec, s[0:1]
	v_cmp_eq_u32_e32 vcc, s33, v191
	v_cmp_eq_u32_e64 s[0:1], s4, v191
	s_or_b64 s[72:73], vcc, s[0:1]
	v_cmp_lt_i32_e64 s[74:75], s33, v191
	s_nor_b64 s[2:3], s[74:75], s[72:73]
	v_mov_b32_e32 v10, 0
	v_mov_b32_e32 v11, 0
	s_and_saveexec_b64 s[0:1], s[2:3]
	s_cbranch_execz .LBB0_1382
	v_mov_b32_e32 v11, v114
	s_nop 0
	v_max_f32_e32 v11, v11, v11
	v_max_f32_e32 v11, 0, v11
	v_add_u32_e32 v11, 1, v11
.LBB0_1382:
	s_or_b64 exec, exec, s[0:1]
	v_cmp_eq_u32_e32 vcc, s33, v192
	v_cmp_eq_u32_e64 s[0:1], s4, v192
	s_or_b64 s[76:77], vcc, s[0:1]
	v_cmp_lt_i32_e64 s[78:79], s33, v192
	s_nor_b64 s[2:3], s[78:79], s[76:77]
	s_and_saveexec_b64 s[0:1], s[2:3]
	s_cbranch_execz .LBB0_1384
	v_mov_b32_e32 v10, v115
	s_nop 0
	v_max_f32_e32 v10, v10, v10
	v_max_f32_e32 v10, 0, v10
	v_add_u32_e32 v10, 1, v10
.LBB0_1384:
	s_or_b64 exec, exec, s[0:1]
	v_cmp_eq_u32_e32 vcc, s33, v193
	v_cmp_eq_u32_e64 s[0:1], s4, v193
	s_or_b64 s[88:89], vcc, s[0:1]
	v_cmp_lt_i32_e64 s[90:91], s33, v193
	s_nor_b64 s[2:3], s[90:91], s[88:89]
	v_mov_b32_e32 v12, 0
	v_mov_b32_e32 v13, 0
	s_and_saveexec_b64 s[0:1], s[2:3]
	s_cbranch_execz .LBB0_1386
	v_mov_b32_e32 v13, v116
	s_nop 0
	v_max_f32_e32 v13, v13, v13
	v_max_f32_e32 v13, 0, v13
	v_add_u32_e32 v13, 1, v13
.LBB0_1386:
	s_or_b64 exec, exec, s[0:1]
	v_cmp_eq_u32_e32 vcc, s33, v194
	v_cmp_eq_u32_e64 s[0:1], s4, v194
	s_or_b64 s[92:93], vcc, s[0:1]
	v_cmp_lt_i32_e64 s[0:1], s33, v194
	s_nop 1
	v_writelane_b32 v247, s0, 50
	s_nor_b64 s[2:3], s[0:1], s[92:93]
	s_nop 0
	v_writelane_b32 v247, s1, 51
	s_and_saveexec_b64 s[0:1], s[2:3]
	s_cbranch_execz .LBB0_1388
	v_mov_b32_e32 v12, v117
	s_nop 0
	v_max_f32_e32 v12, v12, v12
	v_max_f32_e32 v12, 0, v12
	v_add_u32_e32 v12, 1, v12
.LBB0_1388:
	s_or_b64 exec, exec, s[0:1]
	v_cmp_eq_u32_e32 vcc, s33, v195
	v_cmp_eq_u32_e64 s[0:1], s4, v195
	s_or_b64 s[0:1], vcc, s[0:1]
	v_cmp_lt_i32_e64 s[2:3], s33, v195
	v_writelane_b32 v247, s0, 16
	v_mov_b32_e32 v14, 0
	v_mov_b32_e32 v15, 0
	v_writelane_b32 v247, s1, 17
	v_writelane_b32 v247, s2, 12
	s_nop 1
	v_writelane_b32 v247, s3, 13
	s_nor_b64 s[2:3], s[2:3], s[0:1]
	s_and_saveexec_b64 s[0:1], s[2:3]
	s_cbranch_execz .LBB0_1390
	v_mov_b32_e32 v15, v118
	s_nop 0
	v_max_f32_e32 v15, v15, v15
	v_max_f32_e32 v15, 0, v15
	v_add_u32_e32 v15, 1, v15
.LBB0_1390:
	s_or_b64 exec, exec, s[0:1]
	v_cmp_eq_u32_e32 vcc, s33, v196
	v_cmp_eq_u32_e64 s[0:1], s4, v196
	s_or_b64 s[0:1], vcc, s[0:1]
	v_cmp_lt_i32_e64 s[2:3], s33, v196
	v_writelane_b32 v247, s0, 56
	s_nop 1
	v_writelane_b32 v247, s1, 57
	v_writelane_b32 v247, s2, 58
	s_nop 1
	v_writelane_b32 v247, s3, 59
	s_nor_b64 s[2:3], s[2:3], s[0:1]
	s_and_saveexec_b64 s[0:1], s[2:3]
	s_cbranch_execz .LBB0_1392
	v_mov_b32_e32 v14, v119
	s_nop 0
	v_max_f32_e32 v14, v14, v14
	v_max_f32_e32 v14, 0, v14
	v_add_u32_e32 v14, 1, v14
.LBB0_1392:
	s_or_b64 exec, exec, s[0:1]
	v_cmp_eq_u32_e32 vcc, s33, v197
	v_cmp_eq_u32_e64 s[0:1], s4, v197
	s_or_b64 s[0:1], vcc, s[0:1]
	v_cmp_lt_i32_e64 s[2:3], s33, v197
	v_writelane_b32 v247, s0, 60
	v_mov_b32_e32 v16, 0
	v_mov_b32_e32 v17, 0
	v_writelane_b32 v247, s1, 61
	v_writelane_b32 v247, s2, 62
	s_nop 1
	v_writelane_b32 v247, s3, 63
	s_nor_b64 s[2:3], s[2:3], s[0:1]
	s_and_saveexec_b64 s[0:1], s[2:3]
	s_cbranch_execz .LBB0_1394
	v_mov_b32_e32 v17, v120
	s_nop 0
	v_max_f32_e32 v17, v17, v17
	v_max_f32_e32 v17, 0, v17
	v_add_u32_e32 v17, 1, v17
.LBB0_1394:
	s_or_b64 exec, exec, s[0:1]
	v_cmp_eq_u32_e32 vcc, s33, v198
	v_cmp_eq_u32_e64 s[0:1], s4, v198
	s_or_b64 s[4:5], vcc, s[0:1]
	v_cmp_lt_i32_e64 s[0:1], s33, v198
	s_nop 1
	v_writelane_b32 v247, s0, 18
	s_nor_b64 s[2:3], s[0:1], s[4:5]
	s_nop 0
	v_writelane_b32 v247, s1, 19
	s_and_saveexec_b64 s[0:1], s[2:3]
	s_cbranch_execz .LBB0_1396
	v_mov_b32_e32 v16, v121
	s_nop 0
	v_max_f32_e32 v16, v16, v16
	v_max_f32_e32 v16, 0, v16
	v_add_u32_e32 v16, 1, v16
